# nt hint on the layer-0 out-projection epilogue's f32 input row loads (read once, never again)
# speedup vs baseline: 1.0008x; 1.0008x over previous
.Lfo_first:
	s_lshr_b32 s14, s34, 3
	s_mul_i32 s14, s14, 0x3000
	s_add_u32 s16, s86, s14
	s_addc_u32 s17, s87, 0
	s_add_u32 s16, s16, 0x2000
	s_addc_u32 s17, s17, 0
	s_add_u32 s86, s88, s14
	s_addc_u32 s87, s89, 0
	s_add_u32 s86, s86, 0x1000
	s_addc_u32 s87, s87, 0
	v_lshl_add_u32 v171, v170, 1, v96
	v_lshl_add_u32 v171, v222, 11, v171
	v_lshlrev_b32_e32 v170, 2, v170
	s_lshl_b32 s14, s34, 8
	s_add_i32 s14, s14, s81
	s_mov_b64 s[12:13], s[18:19]
	s_lshl_b32 s31, s14, 12
	s_lshl_b32 s14, s14, 11
	s_add_u32 s2, s2, s14
	s_addc_u32 s3, s3, 0
	s_add_u32 s78, s78, s14
	s_addc_u32 s79, s79, 0
	s_add_u32 s22, s78, 0x4000
	s_addc_u32 s23, s79, 0
	s_add_u32 s18, s2, 0x4000
	s_addc_u32 s19, s3, 0
	s_add_u32 s14, s12, s31
	s_addc_u32 s15, s13, 0
	global_load_dwordx4 v[142:145], v170, s[16:17]
	global_load_dwordx4 v[150:153], v170, s[16:17] offset:16
	global_load_dwordx4 v[138:141], v170, s[16:17] offset:128
	global_load_dwordx4 v[146:149], v170, s[16:17] offset:144
	v_lshl_add_u32 v96, v163, 12, v170
	global_load_dwordx4 v[196:199], v96, s[14:15] nt
	global_load_dwordx4 v[200:203], v96, s[14:15] offset:16 nt
	global_load_dwordx4 v[204:207], v96, s[14:15] offset:128 nt
	global_load_dwordx4 v[234:237], v96, s[14:15] offset:144 nt
	global_load_dwordx4 v[180:183], v170, s[86:87]
	global_load_dwordx4 v[184:187], v170, s[86:87] offset:16
	global_load_dwordx4 v[188:191], v170, s[86:87] offset:128
	global_load_dwordx4 v[192:195], v170, s[86:87] offset:144
	global_load_dwordx4 v[238:241], v170, s[26:27]
	global_load_dwordx4 v[242:245], v170, s[26:27] offset:16
	global_load_dwordx4 v[246:249], v170, s[26:27] offset:128
	global_load_dwordx4 v[4:7], v170, s[26:27] offset:144
	s_waitcnt vmcnt(0)
	v_pk_add_f32 v[182:183], v[182:183], 1.0 op_sel_hi:[1,0]
	v_pk_add_f32 v[180:181], v[180:181], 1.0 op_sel_hi:[1,0]
	v_pk_add_f32 v[186:187], v[186:187], 1.0 op_sel_hi:[1,0]
	v_pk_add_f32 v[184:185], v[184:185], 1.0 op_sel_hi:[1,0]
	v_pk_add_f32 v[190:191], v[190:191], 1.0 op_sel_hi:[1,0]
	v_pk_add_f32 v[188:189], v[188:189], 1.0 op_sel_hi:[1,0]
	v_pk_add_f32 v[194:195], v[194:195], 1.0 op_sel_hi:[1,0]
	v_pk_add_f32 v[192:193], v[192:193], 1.0 op_sel_hi:[1,0]
	v_pk_mul_f32 v[182:183], v[240:241], v[182:183]
	v_pk_mul_f32 v[180:181], v[238:239], v[180:181]
	v_pk_mul_f32 v[186:187], v[244:245], v[186:187]
	v_pk_mul_f32 v[184:185], v[242:243], v[184:185]
	v_pk_mul_f32 v[190:191], v[248:249], v[190:191]
	v_pk_mul_f32 v[188:189], v[246:247], v[188:189]
	v_pk_mul_f32 v[194:195], v[6:7], v[194:195]
	v_pk_mul_f32 v[192:193], v[4:5], v[192:193]
	s_add_u32 s14, s14, 0x10000
	s_addc_u32 s15, s15, 0
	global_load_dwordx4 v[238:241], v96, s[14:15] nt
	global_load_dwordx4 v[242:245], v96, s[14:15] offset:16 nt
	v_pk_fma_f32 v[134:135], v[134:135], v[142:143], v[196:197]
	v_pk_fma_f32 v[136:137], v[136:137], v[144:145], v[198:199]
	v_pk_fma_f32 v[130:131], v[130:131], v[150:151], v[200:201]
	v_pk_fma_f32 v[132:133], v[132:133], v[152:153], v[202:203]
	v_pk_fma_f32 v[126:127], v[126:127], v[138:139], v[204:205]
	v_pk_fma_f32 v[128:129], v[128:129], v[140:141], v[206:207]
	v_pk_fma_f32 v[122:123], v[122:123], v[146:147], v[234:235]
	v_pk_fma_f32 v[124:125], v[124:125], v[148:149], v[236:237]
	global_load_dwordx4 v[196:199], v96, s[14:15] offset:128 nt
	global_load_dwordx4 v[200:203], v96, s[14:15] offset:144 nt
	s_add_u32 s14, s14, 0x10000
	s_addc_u32 s15, s15, 0
	global_load_dwordx4 v[204:207], v96, s[14:15] nt
	global_load_dwordx4 v[234:237], v96, s[14:15] offset:16 nt
	v_cvt_pk_bf16_f32 v0, v134, v135
	v_cvt_pk_bf16_f32 v1, v136, v137
	v_cvt_pk_bf16_f32 v2, v130, v131
	v_cvt_pk_bf16_f32 v3, v132, v133
	v_cvt_pk_bf16_f32 v4, v126, v127
	v_cvt_pk_bf16_f32 v5, v128, v129
	v_cvt_pk_bf16_f32 v6, v122, v123
	v_cvt_pk_bf16_f32 v7, v124, v125
	v_mul_f32_e32 v246, v135, v135
	v_mul_f32_e32 v248, v137, v137
	v_fmac_f32_e32 v246, v134, v134
	v_fmac_f32_e32 v248, v136, v136
	v_add_f32_e32 v246, v246, v248
	v_mul_f32_e32 v248, v131, v131
	v_fmac_f32_e32 v248, v130, v130
	v_add_f32_e32 v246, v246, v248
	v_mul_f32_e32 v248, v133, v133
	v_fmac_f32_e32 v248, v132, v132
	v_add_f32_e32 v246, v248, v246
	v_mul_f32_e32 v247, v127, v127
	v_mul_f32_e32 v248, v129, v129
	v_fmac_f32_e32 v247, v126, v126
	v_fmac_f32_e32 v248, v128, v128
	v_add_f32_e32 v247, v247, v248
	v_mul_f32_e32 v248, v123, v123
	v_fmac_f32_e32 v248, v122, v122
	v_add_f32_e32 v247, v247, v248
	v_mul_f32_e32 v248, v125, v125
	v_fmac_f32_e32 v248, v124, v124
	v_add_f32_e32 v247, v248, v247
	v_add_f32_e32 v246, v246, v247
	v_mov_b32_e32 v247, v246
	s_nop 1
	v_permlane16_swap_b32_e32 v246, v247
	s_nop 1
	v_add_f32_e32 v246, v246, v247
	v_mov_b32_e32 v247, v246
	s_nop 1
	v_permlane32_swap_b32_e32 v246, v247
	v_add_u32_e32 v248, s8, v223
	s_nop 0
	v_add_f32_e32 v246, v246, v247
	s_mov_b64 exec, s[44:45]
	ds_write_b32 v248, v246
	s_mov_b64 exec, -1
	v_pk_mul_f32 v[134:135], v[180:181], v[134:135]
	v_pk_mul_f32 v[136:137], v[182:183], v[136:137]
	v_pk_mul_f32 v[130:131], v[184:185], v[130:131]
	v_pk_mul_f32 v[132:133], v[186:187], v[132:133]
	v_pk_mul_f32 v[126:127], v[188:189], v[126:127]
	v_pk_mul_f32 v[128:129], v[190:191], v[128:129]
	v_pk_mul_f32 v[122:123], v[192:193], v[122:123]
	v_pk_mul_f32 v[124:125], v[194:195], v[124:125]
	v_cvt_pk_bf16_f32 v246, v134, v135
	v_cvt_pk_bf16_f32 v247, v136, v137
	v_cvt_pk_bf16_f32 v248, v130, v131
	v_cvt_pk_bf16_f32 v249, v132, v133
	v_cvt_pk_bf16_f32 v250, v126, v127
	v_cvt_pk_bf16_f32 v251, v128, v129
	v_cvt_pk_bf16_f32 v208, v122, v123
	v_cvt_pk_bf16_f32 v209, v124, v125
	s_nop 1
	s_mov_b64 vcc, s[6:7]
	v_cndmask_b32_dpp v134, v4, v0, vcc row_ror:8 row_mask:0xf bank_mask:0xf
	v_cndmask_b32_dpp v135, v5, v1, vcc row_ror:8 row_mask:0xf bank_mask:0xf
	v_cndmask_b32_dpp v136, v6, v2, vcc row_ror:8 row_mask:0xf bank_mask:0xf
	v_cndmask_b32_dpp v137, v7, v3, vcc row_ror:8 row_mask:0xf bank_mask:0xf
	v_cndmask_b32_dpp v126, v250, v246, vcc row_ror:8 row_mask:0xf bank_mask:0xf
	v_cndmask_b32_dpp v127, v251, v247, vcc row_ror:8 row_mask:0xf bank_mask:0xf
	v_cndmask_b32_dpp v128, v208, v248, vcc row_ror:8 row_mask:0xf bank_mask:0xf
	v_cndmask_b32_dpp v129, v209, v249, vcc row_ror:8 row_mask:0xf bank_mask:0xf
	s_not_b64 vcc, s[6:7]
	v_cndmask_b32_dpp v130, v0, v4, vcc row_ror:8 row_mask:0xf bank_mask:0xf
	v_cndmask_b32_dpp v131, v1, v5, vcc row_ror:8 row_mask:0xf bank_mask:0xf
	v_cndmask_b32_dpp v132, v2, v6, vcc row_ror:8 row_mask:0xf bank_mask:0xf
	v_cndmask_b32_dpp v133, v3, v7, vcc row_ror:8 row_mask:0xf bank_mask:0xf
	v_cndmask_b32_dpp v122, v246, v250, vcc row_ror:8 row_mask:0xf bank_mask:0xf
	v_cndmask_b32_dpp v123, v247, v251, vcc row_ror:8 row_mask:0xf bank_mask:0xf
	v_cndmask_b32_dpp v124, v248, v208, vcc row_ror:8 row_mask:0xf bank_mask:0xf
	v_cndmask_b32_dpp v125, v249, v209, vcc row_ror:8 row_mask:0xf bank_mask:0xf
	global_store_dwordx4 v171, v[134:137], s[2:3]
	global_store_dwordx4 v171, v[130:133], s[18:19]
	global_store_dwordx4 v171, v[126:129], s[78:79]
	global_store_dwordx4 v171, v[122:125], s[22:23]
	s_waitcnt vmcnt(6)
	v_pk_fma_f32 v[118:119], v[118:119], v[142:143], v[238:239]
	v_pk_fma_f32 v[120:121], v[120:121], v[144:145], v[240:241]
	v_pk_fma_f32 v[114:115], v[114:115], v[150:151], v[242:243]
	v_pk_fma_f32 v[116:117], v[116:117], v[152:153], v[244:245]
	v_pk_fma_f32 v[110:111], v[110:111], v[138:139], v[196:197]
	v_pk_fma_f32 v[112:113], v[112:113], v[140:141], v[198:199]
	v_pk_fma_f32 v[106:107], v[106:107], v[146:147], v[200:201]
	v_pk_fma_f32 v[108:109], v[108:109], v[148:149], v[202:203]
	global_load_dwordx4 v[238:241], v96, s[14:15] offset:128 nt
	global_load_dwordx4 v[242:245], v96, s[14:15] offset:144 nt
	s_add_u32 s14, s14, 0x10000
	s_addc_u32 s15, s15, 0
	global_load_dwordx4 v[196:199], v96, s[14:15] nt
	global_load_dwordx4 v[200:203], v96, s[14:15] offset:16 nt
	v_cvt_pk_bf16_f32 v0, v118, v119
	v_cvt_pk_bf16_f32 v1, v120, v121
	v_cvt_pk_bf16_f32 v2, v114, v115
	v_cvt_pk_bf16_f32 v3, v116, v117
	v_cvt_pk_bf16_f32 v4, v110, v111
	v_cvt_pk_bf16_f32 v5, v112, v113
	v_cvt_pk_bf16_f32 v6, v106, v107
	v_cvt_pk_bf16_f32 v7, v108, v109
	v_mul_f32_e32 v246, v119, v119
	v_mul_f32_e32 v248, v121, v121
	v_fmac_f32_e32 v246, v118, v118
	v_fmac_f32_e32 v248, v120, v120
	v_add_f32_e32 v246, v246, v248
	v_mul_f32_e32 v248, v115, v115
	v_fmac_f32_e32 v248, v114, v114
	v_add_f32_e32 v246, v246, v248
	v_mul_f32_e32 v248, v117, v117
	v_fmac_f32_e32 v248, v116, v116
	v_add_f32_e32 v246, v248, v246
	v_mul_f32_e32 v247, v111, v111
	v_mul_f32_e32 v248, v113, v113
	v_fmac_f32_e32 v247, v110, v110
	v_fmac_f32_e32 v248, v112, v112
	v_add_f32_e32 v247, v247, v248
	v_mul_f32_e32 v248, v107, v107
	v_fmac_f32_e32 v248, v106, v106
	v_add_f32_e32 v247, v247, v248
	v_mul_f32_e32 v248, v109, v109
	v_fmac_f32_e32 v248, v108, v108
	v_add_f32_e32 v247, v248, v247
	v_add_f32_e32 v246, v246, v247
	v_mov_b32_e32 v247, v246
	s_nop 1
	v_permlane16_swap_b32_e32 v246, v247
	s_nop 1
	v_add_f32_e32 v246, v246, v247
	v_mov_b32_e32 v247, v246
	s_nop 1
	v_permlane32_swap_b32_e32 v246, v247
	v_add_u32_e32 v248, s8, v223
	s_nop 0
	v_add_f32_e32 v246, v246, v247
	s_mov_b64 exec, s[44:45]
	ds_write_b32 v248, v246 offset:256
	s_mov_b64 exec, -1
	v_pk_mul_f32 v[118:119], v[180:181], v[118:119]
	v_pk_mul_f32 v[120:121], v[182:183], v[120:121]
	v_pk_mul_f32 v[114:115], v[184:185], v[114:115]
	v_pk_mul_f32 v[116:117], v[186:187], v[116:117]
	v_pk_mul_f32 v[110:111], v[188:189], v[110:111]
	v_pk_mul_f32 v[112:113], v[190:191], v[112:113]
	v_pk_mul_f32 v[106:107], v[192:193], v[106:107]
	v_pk_mul_f32 v[108:109], v[194:195], v[108:109]
	v_cvt_pk_bf16_f32 v246, v118, v119
	v_cvt_pk_bf16_f32 v247, v120, v121
	v_cvt_pk_bf16_f32 v248, v114, v115
	v_cvt_pk_bf16_f32 v249, v116, v117
	v_cvt_pk_bf16_f32 v250, v110, v111
	v_cvt_pk_bf16_f32 v251, v112, v113
	v_cvt_pk_bf16_f32 v208, v106, v107
	v_cvt_pk_bf16_f32 v209, v108, v109
	s_add_u32 s2, s2, 0x8000
	s_addc_u32 s3, s3, 0
	s_add_u32 s18, s18, 0x8000
	s_addc_u32 s19, s19, 0
	s_add_u32 s78, s78, 0x8000
	s_addc_u32 s79, s79, 0
	s_add_u32 s22, s22, 0x8000
	s_addc_u32 s23, s23, 0
	s_mov_b64 vcc, s[6:7]
	v_cndmask_b32_dpp v118, v4, v0, vcc row_ror:8 row_mask:0xf bank_mask:0xf
	v_cndmask_b32_dpp v119, v5, v1, vcc row_ror:8 row_mask:0xf bank_mask:0xf
	v_cndmask_b32_dpp v120, v6, v2, vcc row_ror:8 row_mask:0xf bank_mask:0xf
	v_cndmask_b32_dpp v121, v7, v3, vcc row_ror:8 row_mask:0xf bank_mask:0xf
	v_cndmask_b32_dpp v110, v250, v246, vcc row_ror:8 row_mask:0xf bank_mask:0xf
	v_cndmask_b32_dpp v111, v251, v247, vcc row_ror:8 row_mask:0xf bank_mask:0xf
	v_cndmask_b32_dpp v112, v208, v248, vcc row_ror:8 row_mask:0xf bank_mask:0xf
	v_cndmask_b32_dpp v113, v209, v249, vcc row_ror:8 row_mask:0xf bank_mask:0xf
	s_not_b64 vcc, s[6:7]
	v_cndmask_b32_dpp v114, v0, v4, vcc row_ror:8 row_mask:0xf bank_mask:0xf
	v_cndmask_b32_dpp v115, v1, v5, vcc row_ror:8 row_mask:0xf bank_mask:0xf
	v_cndmask_b32_dpp v116, v2, v6, vcc row_ror:8 row_mask:0xf bank_mask:0xf
	v_cndmask_b32_dpp v117, v3, v7, vcc row_ror:8 row_mask:0xf bank_mask:0xf
	v_cndmask_b32_dpp v106, v246, v250, vcc row_ror:8 row_mask:0xf bank_mask:0xf
	v_cndmask_b32_dpp v107, v247, v251, vcc row_ror:8 row_mask:0xf bank_mask:0xf
	v_cndmask_b32_dpp v108, v248, v208, vcc row_ror:8 row_mask:0xf bank_mask:0xf
	v_cndmask_b32_dpp v109, v249, v209, vcc row_ror:8 row_mask:0xf bank_mask:0xf
	global_store_dwordx4 v171, v[118:121], s[2:3]
	global_store_dwordx4 v171, v[114:117], s[18:19]
	global_store_dwordx4 v171, v[110:113], s[78:79]
	global_store_dwordx4 v171, v[106:109], s[22:23]
	s_waitcnt vmcnt(6)
	v_pk_fma_f32 v[102:103], v[102:103], v[142:143], v[204:205]
	v_pk_fma_f32 v[104:105], v[104:105], v[144:145], v[206:207]
	v_pk_fma_f32 v[98:99], v[98:99], v[150:151], v[234:235]
	v_pk_fma_f32 v[100:101], v[100:101], v[152:153], v[236:237]
	v_pk_fma_f32 v[92:93], v[92:93], v[138:139], v[238:239]
	v_pk_fma_f32 v[94:95], v[94:95], v[140:141], v[240:241]
	v_pk_fma_f32 v[88:89], v[88:89], v[146:147], v[242:243]
	v_pk_fma_f32 v[90:91], v[90:91], v[148:149], v[244:245]
	global_load_dwordx4 v[204:207], v96, s[14:15] offset:128 nt
	global_load_dwordx4 v[234:237], v96, s[14:15] offset:144 nt
	s_add_u32 s14, s14, 0x50000
	s_addc_u32 s15, s15, 0
	global_load_dwordx4 v[238:241], v96, s[14:15] nt
	global_load_dwordx4 v[242:245], v96, s[14:15] offset:16 nt
	v_cvt_pk_bf16_f32 v0, v102, v103
	v_cvt_pk_bf16_f32 v1, v104, v105
	v_cvt_pk_bf16_f32 v2, v98, v99
	v_cvt_pk_bf16_f32 v3, v100, v101
	v_cvt_pk_bf16_f32 v4, v92, v93
	v_cvt_pk_bf16_f32 v5, v94, v95
	v_cvt_pk_bf16_f32 v6, v88, v89
	v_cvt_pk_bf16_f32 v7, v90, v91
	v_mul_f32_e32 v246, v103, v103
	v_mul_f32_e32 v248, v105, v105
	v_fmac_f32_e32 v246, v102, v102
	v_fmac_f32_e32 v248, v104, v104
	v_add_f32_e32 v246, v246, v248
	v_mul_f32_e32 v248, v99, v99
	v_fmac_f32_e32 v248, v98, v98
	v_add_f32_e32 v246, v246, v248
	v_mul_f32_e32 v248, v101, v101
	v_fmac_f32_e32 v248, v100, v100
	v_add_f32_e32 v246, v248, v246
	v_mul_f32_e32 v247, v93, v93
	v_mul_f32_e32 v248, v95, v95
	v_fmac_f32_e32 v247, v92, v92
	v_fmac_f32_e32 v248, v94, v94
	v_add_f32_e32 v247, v247, v248
	v_mul_f32_e32 v248, v89, v89
	v_fmac_f32_e32 v248, v88, v88
	v_add_f32_e32 v247, v247, v248
	v_mul_f32_e32 v248, v91, v91
	v_fmac_f32_e32 v248, v90, v90
	v_add_f32_e32 v247, v248, v247
	v_add_f32_e32 v246, v246, v247
	v_mov_b32_e32 v247, v246
	s_nop 1
	v_permlane16_swap_b32_e32 v246, v247
	s_nop 1
	v_add_f32_e32 v246, v246, v247
	v_mov_b32_e32 v247, v246
	s_nop 1
	v_permlane32_swap_b32_e32 v246, v247
	v_add_u32_e32 v248, s8, v223
	s_nop 0
	v_add_f32_e32 v246, v246, v247
	s_mov_b64 exec, s[44:45]
	ds_write_b32 v248, v246 offset:512
	s_mov_b64 exec, -1
	v_pk_mul_f32 v[102:103], v[180:181], v[102:103]
	v_pk_mul_f32 v[104:105], v[182:183], v[104:105]
	v_pk_mul_f32 v[98:99], v[184:185], v[98:99]
	v_pk_mul_f32 v[100:101], v[186:187], v[100:101]
	v_pk_mul_f32 v[92:93], v[188:189], v[92:93]
	v_pk_mul_f32 v[94:95], v[190:191], v[94:95]
	v_pk_mul_f32 v[88:89], v[192:193], v[88:89]
	v_pk_mul_f32 v[90:91], v[194:195], v[90:91]
	v_cvt_pk_bf16_f32 v246, v102, v103
	v_cvt_pk_bf16_f32 v247, v104, v105
	v_cvt_pk_bf16_f32 v248, v98, v99
	v_cvt_pk_bf16_f32 v249, v100, v101
	v_cvt_pk_bf16_f32 v250, v92, v93
	v_cvt_pk_bf16_f32 v251, v94, v95
	v_cvt_pk_bf16_f32 v208, v88, v89
	v_cvt_pk_bf16_f32 v209, v90, v91
	s_add_u32 s2, s2, 0x8000
	s_addc_u32 s3, s3, 0
	s_add_u32 s18, s18, 0x8000
	s_addc_u32 s19, s19, 0
	s_add_u32 s78, s78, 0x8000
	s_addc_u32 s79, s79, 0
	s_add_u32 s22, s22, 0x8000
	s_addc_u32 s23, s23, 0
	s_mov_b64 vcc, s[6:7]
	v_cndmask_b32_dpp v102, v4, v0, vcc row_ror:8 row_mask:0xf bank_mask:0xf
	v_cndmask_b32_dpp v103, v5, v1, vcc row_ror:8 row_mask:0xf bank_mask:0xf
	v_cndmask_b32_dpp v104, v6, v2, vcc row_ror:8 row_mask:0xf bank_mask:0xf
	v_cndmask_b32_dpp v105, v7, v3, vcc row_ror:8 row_mask:0xf bank_mask:0xf
	v_cndmask_b32_dpp v92, v250, v246, vcc row_ror:8 row_mask:0xf bank_mask:0xf
	v_cndmask_b32_dpp v93, v251, v247, vcc row_ror:8 row_mask:0xf bank_mask:0xf
	v_cndmask_b32_dpp v94, v208, v248, vcc row_ror:8 row_mask:0xf bank_mask:0xf
	v_cndmask_b32_dpp v95, v209, v249, vcc row_ror:8 row_mask:0xf bank_mask:0xf
	s_not_b64 vcc, s[6:7]
	v_cndmask_b32_dpp v98, v0, v4, vcc row_ror:8 row_mask:0xf bank_mask:0xf
	v_cndmask_b32_dpp v99, v1, v5, vcc row_ror:8 row_mask:0xf bank_mask:0xf
	v_cndmask_b32_dpp v100, v2, v6, vcc row_ror:8 row_mask:0xf bank_mask:0xf
	v_cndmask_b32_dpp v101, v3, v7, vcc row_ror:8 row_mask:0xf bank_mask:0xf
	v_cndmask_b32_dpp v88, v246, v250, vcc row_ror:8 row_mask:0xf bank_mask:0xf
	v_cndmask_b32_dpp v89, v247, v251, vcc row_ror:8 row_mask:0xf bank_mask:0xf
	v_cndmask_b32_dpp v90, v248, v208, vcc row_ror:8 row_mask:0xf bank_mask:0xf
	v_cndmask_b32_dpp v91, v249, v209, vcc row_ror:8 row_mask:0xf bank_mask:0xf
	global_store_dwordx4 v171, v[102:105], s[2:3]
	global_store_dwordx4 v171, v[98:101], s[18:19]
	global_store_dwordx4 v171, v[92:95], s[78:79]
	global_store_dwordx4 v171, v[88:91], s[22:23]
	s_waitcnt vmcnt(6)
	v_pk_fma_f32 v[84:85], v[84:85], v[142:143], v[196:197]
	v_pk_fma_f32 v[86:87], v[86:87], v[144:145], v[198:199]
	v_pk_fma_f32 v[80:81], v[80:81], v[150:151], v[200:201]
	v_pk_fma_f32 v[82:83], v[82:83], v[152:153], v[202:203]
	v_pk_fma_f32 v[76:77], v[76:77], v[138:139], v[204:205]
	v_pk_fma_f32 v[78:79], v[78:79], v[140:141], v[206:207]
	v_pk_fma_f32 v[72:73], v[72:73], v[146:147], v[234:235]
	v_pk_fma_f32 v[74:75], v[74:75], v[148:149], v[236:237]
	global_load_dwordx4 v[196:199], v96, s[14:15] offset:128 nt
	global_load_dwordx4 v[200:203], v96, s[14:15] offset:144 nt
	s_add_u32 s14, s14, 0x10000
	s_addc_u32 s15, s15, 0
	global_load_dwordx4 v[204:207], v96, s[14:15] nt
	global_load_dwordx4 v[234:237], v96, s[14:15] offset:16 nt
	v_cvt_pk_bf16_f32 v0, v84, v85
	v_cvt_pk_bf16_f32 v1, v86, v87
	v_cvt_pk_bf16_f32 v2, v80, v81
	v_cvt_pk_bf16_f32 v3, v82, v83
	v_cvt_pk_bf16_f32 v4, v76, v77
	v_cvt_pk_bf16_f32 v5, v78, v79
	v_cvt_pk_bf16_f32 v6, v72, v73
	v_cvt_pk_bf16_f32 v7, v74, v75
	v_mul_f32_e32 v246, v85, v85
	v_mul_f32_e32 v248, v87, v87
	v_fmac_f32_e32 v246, v84, v84
	v_fmac_f32_e32 v248, v86, v86
	v_add_f32_e32 v246, v246, v248
	v_mul_f32_e32 v248, v81, v81
	v_fmac_f32_e32 v248, v80, v80
	v_add_f32_e32 v246, v246, v248
	v_mul_f32_e32 v248, v83, v83
	v_fmac_f32_e32 v248, v82, v82
	v_add_f32_e32 v246, v248, v246
	v_mul_f32_e32 v247, v77, v77
	v_mul_f32_e32 v248, v79, v79
	v_fmac_f32_e32 v247, v76, v76
	v_fmac_f32_e32 v248, v78, v78
	v_add_f32_e32 v247, v247, v248
	v_mul_f32_e32 v248, v73, v73
	v_fmac_f32_e32 v248, v72, v72
	v_add_f32_e32 v247, v247, v248
	v_mul_f32_e32 v248, v75, v75
	v_fmac_f32_e32 v248, v74, v74
	v_add_f32_e32 v247, v248, v247
	v_add_f32_e32 v246, v246, v247
	v_mov_b32_e32 v247, v246
	s_nop 1
	v_permlane16_swap_b32_e32 v246, v247
	s_nop 1
	v_add_f32_e32 v246, v246, v247
	v_mov_b32_e32 v247, v246
	s_nop 1
	v_permlane32_swap_b32_e32 v246, v247
	v_add_u32_e32 v248, s8, v223
	s_nop 0
	v_add_f32_e32 v246, v246, v247
	s_mov_b64 exec, s[44:45]
	ds_write_b32 v248, v246 offset:768
	s_mov_b64 exec, -1
	v_pk_mul_f32 v[84:85], v[180:181], v[84:85]
	v_pk_mul_f32 v[86:87], v[182:183], v[86:87]
	v_pk_mul_f32 v[80:81], v[184:185], v[80:81]
	v_pk_mul_f32 v[82:83], v[186:187], v[82:83]
	v_pk_mul_f32 v[76:77], v[188:189], v[76:77]
	v_pk_mul_f32 v[78:79], v[190:191], v[78:79]
	v_pk_mul_f32 v[72:73], v[192:193], v[72:73]
	v_pk_mul_f32 v[74:75], v[194:195], v[74:75]
	v_cvt_pk_bf16_f32 v246, v84, v85
	v_cvt_pk_bf16_f32 v247, v86, v87
	v_cvt_pk_bf16_f32 v248, v80, v81
	v_cvt_pk_bf16_f32 v249, v82, v83
	v_cvt_pk_bf16_f32 v250, v76, v77
	v_cvt_pk_bf16_f32 v251, v78, v79
	v_cvt_pk_bf16_f32 v208, v72, v73
	v_cvt_pk_bf16_f32 v209, v74, v75
	s_add_u32 s2, s2, 0x8000
	s_addc_u32 s3, s3, 0
	s_add_u32 s18, s18, 0x8000
	s_addc_u32 s19, s19, 0
	s_add_u32 s78, s78, 0x8000
	s_addc_u32 s79, s79, 0
	s_add_u32 s22, s22, 0x8000
	s_addc_u32 s23, s23, 0
	s_mov_b64 vcc, s[6:7]
	v_cndmask_b32_dpp v84, v4, v0, vcc row_ror:8 row_mask:0xf bank_mask:0xf
	v_cndmask_b32_dpp v85, v5, v1, vcc row_ror:8 row_mask:0xf bank_mask:0xf
	v_cndmask_b32_dpp v86, v6, v2, vcc row_ror:8 row_mask:0xf bank_mask:0xf
	v_cndmask_b32_dpp v87, v7, v3, vcc row_ror:8 row_mask:0xf bank_mask:0xf
	v_cndmask_b32_dpp v76, v250, v246, vcc row_ror:8 row_mask:0xf bank_mask:0xf
	v_cndmask_b32_dpp v77, v251, v247, vcc row_ror:8 row_mask:0xf bank_mask:0xf
	v_cndmask_b32_dpp v78, v208, v248, vcc row_ror:8 row_mask:0xf bank_mask:0xf
	v_cndmask_b32_dpp v79, v209, v249, vcc row_ror:8 row_mask:0xf bank_mask:0xf
	s_not_b64 vcc, s[6:7]
	v_cndmask_b32_dpp v80, v0, v4, vcc row_ror:8 row_mask:0xf bank_mask:0xf
	v_cndmask_b32_dpp v81, v1, v5, vcc row_ror:8 row_mask:0xf bank_mask:0xf
	v_cndmask_b32_dpp v82, v2, v6, vcc row_ror:8 row_mask:0xf bank_mask:0xf
	v_cndmask_b32_dpp v83, v3, v7, vcc row_ror:8 row_mask:0xf bank_mask:0xf
	v_cndmask_b32_dpp v72, v246, v250, vcc row_ror:8 row_mask:0xf bank_mask:0xf
	v_cndmask_b32_dpp v73, v247, v251, vcc row_ror:8 row_mask:0xf bank_mask:0xf
	v_cndmask_b32_dpp v74, v248, v208, vcc row_ror:8 row_mask:0xf bank_mask:0xf
	v_cndmask_b32_dpp v75, v249, v209, vcc row_ror:8 row_mask:0xf bank_mask:0xf
	global_store_dwordx4 v171, v[84:87], s[2:3]
	global_store_dwordx4 v171, v[80:83], s[18:19]
	global_store_dwordx4 v171, v[76:79], s[78:79]
	global_store_dwordx4 v171, v[72:75], s[22:23]
	s_waitcnt vmcnt(6)
	v_pk_fma_f32 v[68:69], v[68:69], v[142:143], v[238:239]
	v_pk_fma_f32 v[70:71], v[70:71], v[144:145], v[240:241]
	v_pk_fma_f32 v[64:65], v[64:65], v[150:151], v[242:243]
	v_pk_fma_f32 v[66:67], v[66:67], v[152:153], v[244:245]
	v_pk_fma_f32 v[60:61], v[60:61], v[138:139], v[196:197]
	v_pk_fma_f32 v[62:63], v[62:63], v[140:141], v[198:199]
	v_pk_fma_f32 v[56:57], v[56:57], v[146:147], v[200:201]
	v_pk_fma_f32 v[58:59], v[58:59], v[148:149], v[202:203]
	global_load_dwordx4 v[238:241], v96, s[14:15] offset:128 nt
	global_load_dwordx4 v[242:245], v96, s[14:15] offset:144 nt
	s_add_u32 s14, s14, 0x10000
	s_addc_u32 s15, s15, 0
	global_load_dwordx4 v[196:199], v96, s[14:15] nt
	global_load_dwordx4 v[200:203], v96, s[14:15] offset:16 nt
	v_cvt_pk_bf16_f32 v0, v68, v69
	v_cvt_pk_bf16_f32 v1, v70, v71
	v_cvt_pk_bf16_f32 v2, v64, v65
	v_cvt_pk_bf16_f32 v3, v66, v67
	v_cvt_pk_bf16_f32 v4, v60, v61
	v_cvt_pk_bf16_f32 v5, v62, v63
	v_cvt_pk_bf16_f32 v6, v56, v57
	v_cvt_pk_bf16_f32 v7, v58, v59
	v_mul_f32_e32 v246, v69, v69
	v_mul_f32_e32 v248, v71, v71
	v_fmac_f32_e32 v246, v68, v68
	v_fmac_f32_e32 v248, v70, v70
	v_add_f32_e32 v246, v246, v248
	v_mul_f32_e32 v248, v65, v65
	v_fmac_f32_e32 v248, v64, v64
	v_add_f32_e32 v246, v246, v248
	v_mul_f32_e32 v248, v67, v67
	v_fmac_f32_e32 v248, v66, v66
	v_add_f32_e32 v246, v248, v246
	v_mul_f32_e32 v247, v61, v61
	v_mul_f32_e32 v248, v63, v63
	v_fmac_f32_e32 v247, v60, v60
	v_fmac_f32_e32 v248, v62, v62
	v_add_f32_e32 v247, v247, v248
	v_mul_f32_e32 v248, v57, v57
	v_fmac_f32_e32 v248, v56, v56
	v_add_f32_e32 v247, v247, v248
	v_mul_f32_e32 v248, v59, v59
	v_fmac_f32_e32 v248, v58, v58
	v_add_f32_e32 v247, v248, v247
	v_add_f32_e32 v246, v246, v247
	v_mov_b32_e32 v247, v246
	s_nop 1
	v_permlane16_swap_b32_e32 v246, v247
	s_nop 1
	v_add_f32_e32 v246, v246, v247
	v_mov_b32_e32 v247, v246
	s_nop 1
	v_permlane32_swap_b32_e32 v246, v247
	v_add_u32_e32 v248, s8, v223
	s_nop 0
	v_add_f32_e32 v246, v246, v247
	s_mov_b64 exec, s[44:45]
	ds_write_b32 v248, v246 offset:2048
	s_mov_b64 exec, -1
	v_pk_mul_f32 v[68:69], v[180:181], v[68:69]
	v_pk_mul_f32 v[70:71], v[182:183], v[70:71]
	v_pk_mul_f32 v[64:65], v[184:185], v[64:65]
	v_pk_mul_f32 v[66:67], v[186:187], v[66:67]
	v_pk_mul_f32 v[60:61], v[188:189], v[60:61]
	v_pk_mul_f32 v[62:63], v[190:191], v[62:63]
	v_pk_mul_f32 v[56:57], v[192:193], v[56:57]
	v_pk_mul_f32 v[58:59], v[194:195], v[58:59]
	v_cvt_pk_bf16_f32 v246, v68, v69
	v_cvt_pk_bf16_f32 v247, v70, v71
	v_cvt_pk_bf16_f32 v248, v64, v65
	v_cvt_pk_bf16_f32 v249, v66, v67
	v_cvt_pk_bf16_f32 v250, v60, v61
	v_cvt_pk_bf16_f32 v251, v62, v63
	v_cvt_pk_bf16_f32 v208, v56, v57
	v_cvt_pk_bf16_f32 v209, v58, v59
	s_add_u32 s2, s2, 0x28000
	s_addc_u32 s3, s3, 0
	s_add_u32 s18, s18, 0x28000
	s_addc_u32 s19, s19, 0
	s_add_u32 s78, s78, 0x28000
	s_addc_u32 s79, s79, 0
	s_add_u32 s22, s22, 0x28000
	s_addc_u32 s23, s23, 0
	s_mov_b64 vcc, s[6:7]
	v_cndmask_b32_dpp v68, v4, v0, vcc row_ror:8 row_mask:0xf bank_mask:0xf
	v_cndmask_b32_dpp v69, v5, v1, vcc row_ror:8 row_mask:0xf bank_mask:0xf
	v_cndmask_b32_dpp v70, v6, v2, vcc row_ror:8 row_mask:0xf bank_mask:0xf
	v_cndmask_b32_dpp v71, v7, v3, vcc row_ror:8 row_mask:0xf bank_mask:0xf
	v_cndmask_b32_dpp v60, v250, v246, vcc row_ror:8 row_mask:0xf bank_mask:0xf
	v_cndmask_b32_dpp v61, v251, v247, vcc row_ror:8 row_mask:0xf bank_mask:0xf
	v_cndmask_b32_dpp v62, v208, v248, vcc row_ror:8 row_mask:0xf bank_mask:0xf
	v_cndmask_b32_dpp v63, v209, v249, vcc row_ror:8 row_mask:0xf bank_mask:0xf
	s_not_b64 vcc, s[6:7]
	v_cndmask_b32_dpp v64, v0, v4, vcc row_ror:8 row_mask:0xf bank_mask:0xf
	v_cndmask_b32_dpp v65, v1, v5, vcc row_ror:8 row_mask:0xf bank_mask:0xf
	v_cndmask_b32_dpp v66, v2, v6, vcc row_ror:8 row_mask:0xf bank_mask:0xf
	v_cndmask_b32_dpp v67, v3, v7, vcc row_ror:8 row_mask:0xf bank_mask:0xf
	v_cndmask_b32_dpp v56, v246, v250, vcc row_ror:8 row_mask:0xf bank_mask:0xf
	v_cndmask_b32_dpp v57, v247, v251, vcc row_ror:8 row_mask:0xf bank_mask:0xf
	v_cndmask_b32_dpp v58, v248, v208, vcc row_ror:8 row_mask:0xf bank_mask:0xf
	v_cndmask_b32_dpp v59, v249, v209, vcc row_ror:8 row_mask:0xf bank_mask:0xf
	global_store_dwordx4 v171, v[68:71], s[2:3]
	global_store_dwordx4 v171, v[64:67], s[18:19]
	global_store_dwordx4 v171, v[60:63], s[78:79]
	global_store_dwordx4 v171, v[56:59], s[22:23]
	s_waitcnt vmcnt(6)
	v_pk_fma_f32 v[52:53], v[52:53], v[142:143], v[204:205]
	v_pk_fma_f32 v[54:55], v[54:55], v[144:145], v[206:207]
	v_pk_fma_f32 v[48:49], v[48:49], v[150:151], v[234:235]
	v_pk_fma_f32 v[50:51], v[50:51], v[152:153], v[236:237]
	v_pk_fma_f32 v[44:45], v[44:45], v[138:139], v[238:239]
	v_pk_fma_f32 v[46:47], v[46:47], v[140:141], v[240:241]
	v_pk_fma_f32 v[40:41], v[40:41], v[146:147], v[242:243]
	v_pk_fma_f32 v[42:43], v[42:43], v[148:149], v[244:245]
	global_load_dwordx4 v[204:207], v96, s[14:15] offset:128 nt
	global_load_dwordx4 v[234:237], v96, s[14:15] offset:144 nt
	s_add_u32 s14, s14, 0x10000
	s_addc_u32 s15, s15, 0
	global_load_dwordx4 v[238:241], v96, s[14:15] nt
	global_load_dwordx4 v[242:245], v96, s[14:15] offset:16 nt
	v_cvt_pk_bf16_f32 v0, v52, v53
	v_cvt_pk_bf16_f32 v1, v54, v55
	v_cvt_pk_bf16_f32 v2, v48, v49
	v_cvt_pk_bf16_f32 v3, v50, v51
	v_cvt_pk_bf16_f32 v4, v44, v45
	v_cvt_pk_bf16_f32 v5, v46, v47
	v_cvt_pk_bf16_f32 v6, v40, v41
	v_cvt_pk_bf16_f32 v7, v42, v43
	v_mul_f32_e32 v246, v53, v53
	v_mul_f32_e32 v248, v55, v55
	v_fmac_f32_e32 v246, v52, v52
	v_fmac_f32_e32 v248, v54, v54
	v_add_f32_e32 v246, v246, v248
	v_mul_f32_e32 v248, v49, v49
	v_fmac_f32_e32 v248, v48, v48
	v_add_f32_e32 v246, v246, v248
	v_mul_f32_e32 v248, v51, v51
	v_fmac_f32_e32 v248, v50, v50
	v_add_f32_e32 v246, v248, v246
	v_mul_f32_e32 v247, v45, v45
	v_mul_f32_e32 v248, v47, v47
	v_fmac_f32_e32 v247, v44, v44
	v_fmac_f32_e32 v248, v46, v46
	v_add_f32_e32 v247, v247, v248
	v_mul_f32_e32 v248, v41, v41
	v_fmac_f32_e32 v248, v40, v40
	v_add_f32_e32 v247, v247, v248
	v_mul_f32_e32 v248, v43, v43
	v_fmac_f32_e32 v248, v42, v42
	v_add_f32_e32 v247, v248, v247
	v_add_f32_e32 v246, v246, v247
	v_mov_b32_e32 v247, v246
	s_nop 1
	v_permlane16_swap_b32_e32 v246, v247
	s_nop 1
	v_add_f32_e32 v246, v246, v247
	v_mov_b32_e32 v247, v246
	s_nop 1
	v_permlane32_swap_b32_e32 v246, v247
	v_add_u32_e32 v248, s8, v223
	s_nop 0
	v_add_f32_e32 v246, v246, v247
	s_mov_b64 exec, s[44:45]
	ds_write_b32 v248, v246 offset:2304
	s_mov_b64 exec, -1
	v_pk_mul_f32 v[52:53], v[180:181], v[52:53]
	v_pk_mul_f32 v[54:55], v[182:183], v[54:55]
	v_pk_mul_f32 v[48:49], v[184:185], v[48:49]
	v_pk_mul_f32 v[50:51], v[186:187], v[50:51]
	v_pk_mul_f32 v[44:45], v[188:189], v[44:45]
	v_pk_mul_f32 v[46:47], v[190:191], v[46:47]
	v_pk_mul_f32 v[40:41], v[192:193], v[40:41]
	v_pk_mul_f32 v[42:43], v[194:195], v[42:43]
	v_cvt_pk_bf16_f32 v246, v52, v53
	v_cvt_pk_bf16_f32 v247, v54, v55
	v_cvt_pk_bf16_f32 v248, v48, v49
	v_cvt_pk_bf16_f32 v249, v50, v51
	v_cvt_pk_bf16_f32 v250, v44, v45
	v_cvt_pk_bf16_f32 v251, v46, v47
	v_cvt_pk_bf16_f32 v208, v40, v41
	v_cvt_pk_bf16_f32 v209, v42, v43
	s_add_u32 s2, s2, 0x8000
	s_addc_u32 s3, s3, 0
	s_add_u32 s18, s18, 0x8000
	s_addc_u32 s19, s19, 0
	s_add_u32 s78, s78, 0x8000
	s_addc_u32 s79, s79, 0
	s_add_u32 s22, s22, 0x8000
	s_addc_u32 s23, s23, 0
	s_mov_b64 vcc, s[6:7]
	v_cndmask_b32_dpp v52, v4, v0, vcc row_ror:8 row_mask:0xf bank_mask:0xf
	v_cndmask_b32_dpp v53, v5, v1, vcc row_ror:8 row_mask:0xf bank_mask:0xf
	v_cndmask_b32_dpp v54, v6, v2, vcc row_ror:8 row_mask:0xf bank_mask:0xf
	v_cndmask_b32_dpp v55, v7, v3, vcc row_ror:8 row_mask:0xf bank_mask:0xf
	v_cndmask_b32_dpp v44, v250, v246, vcc row_ror:8 row_mask:0xf bank_mask:0xf
	v_cndmask_b32_dpp v45, v251, v247, vcc row_ror:8 row_mask:0xf bank_mask:0xf
	v_cndmask_b32_dpp v46, v208, v248, vcc row_ror:8 row_mask:0xf bank_mask:0xf
	v_cndmask_b32_dpp v47, v209, v249, vcc row_ror:8 row_mask:0xf bank_mask:0xf
	s_not_b64 vcc, s[6:7]
	v_cndmask_b32_dpp v48, v0, v4, vcc row_ror:8 row_mask:0xf bank_mask:0xf
	v_cndmask_b32_dpp v49, v1, v5, vcc row_ror:8 row_mask:0xf bank_mask:0xf
	v_cndmask_b32_dpp v50, v2, v6, vcc row_ror:8 row_mask:0xf bank_mask:0xf
	v_cndmask_b32_dpp v51, v3, v7, vcc row_ror:8 row_mask:0xf bank_mask:0xf
	v_cndmask_b32_dpp v40, v246, v250, vcc row_ror:8 row_mask:0xf bank_mask:0xf
	v_cndmask_b32_dpp v41, v247, v251, vcc row_ror:8 row_mask:0xf bank_mask:0xf
	v_cndmask_b32_dpp v42, v248, v208, vcc row_ror:8 row_mask:0xf bank_mask:0xf
	v_cndmask_b32_dpp v43, v249, v209, vcc row_ror:8 row_mask:0xf bank_mask:0xf
	global_store_dwordx4 v171, v[52:55], s[2:3]
	global_store_dwordx4 v171, v[48:51], s[18:19]
	global_store_dwordx4 v171, v[44:47], s[78:79]
	global_store_dwordx4 v171, v[40:43], s[22:23]
	s_waitcnt vmcnt(6)
	v_pk_fma_f32 v[36:37], v[36:37], v[142:143], v[196:197]
	v_pk_fma_f32 v[38:39], v[38:39], v[144:145], v[198:199]
	v_pk_fma_f32 v[32:33], v[32:33], v[150:151], v[200:201]
	v_pk_fma_f32 v[34:35], v[34:35], v[152:153], v[202:203]
	v_pk_fma_f32 v[28:29], v[28:29], v[138:139], v[204:205]
	v_pk_fma_f32 v[30:31], v[30:31], v[140:141], v[206:207]
	v_pk_fma_f32 v[24:25], v[24:25], v[146:147], v[234:235]
	v_pk_fma_f32 v[26:27], v[26:27], v[148:149], v[236:237]
	global_load_dwordx4 v[196:199], v96, s[14:15] offset:128 nt
	global_load_dwordx4 v[200:203], v96, s[14:15] offset:144 nt
	v_cvt_pk_bf16_f32 v0, v36, v37
	v_cvt_pk_bf16_f32 v1, v38, v39
	v_cvt_pk_bf16_f32 v2, v32, v33
	v_cvt_pk_bf16_f32 v3, v34, v35
	v_cvt_pk_bf16_f32 v4, v28, v29
	v_cvt_pk_bf16_f32 v5, v30, v31
	v_cvt_pk_bf16_f32 v6, v24, v25
	v_cvt_pk_bf16_f32 v7, v26, v27
	v_mul_f32_e32 v246, v37, v37
	v_mul_f32_e32 v248, v39, v39
	v_fmac_f32_e32 v246, v36, v36
	v_fmac_f32_e32 v248, v38, v38
	v_add_f32_e32 v246, v246, v248
	v_mul_f32_e32 v248, v33, v33
	v_fmac_f32_e32 v248, v32, v32
	v_add_f32_e32 v246, v246, v248
	v_mul_f32_e32 v248, v35, v35
	v_fmac_f32_e32 v248, v34, v34
	v_add_f32_e32 v246, v248, v246
	v_mul_f32_e32 v247, v29, v29
	v_mul_f32_e32 v248, v31, v31
	v_fmac_f32_e32 v247, v28, v28
	v_fmac_f32_e32 v248, v30, v30
	v_add_f32_e32 v247, v247, v248
	v_mul_f32_e32 v248, v25, v25
	v_fmac_f32_e32 v248, v24, v24
	v_add_f32_e32 v247, v247, v248
	v_mul_f32_e32 v248, v27, v27
	v_fmac_f32_e32 v248, v26, v26
	v_add_f32_e32 v247, v248, v247
	v_add_f32_e32 v246, v246, v247
	v_mov_b32_e32 v247, v246
	s_nop 1
	v_permlane16_swap_b32_e32 v246, v247
	s_nop 1
	v_add_f32_e32 v246, v246, v247
	v_mov_b32_e32 v247, v246
	s_nop 1
	v_permlane32_swap_b32_e32 v246, v247
	v_add_u32_e32 v248, s8, v223
	s_nop 0
	v_add_f32_e32 v246, v246, v247
	s_mov_b64 exec, s[44:45]
	ds_write_b32 v248, v246 offset:2560
	s_mov_b64 exec, -1
	v_pk_mul_f32 v[36:37], v[180:181], v[36:37]
	v_pk_mul_f32 v[38:39], v[182:183], v[38:39]
	v_pk_mul_f32 v[32:33], v[184:185], v[32:33]
	v_pk_mul_f32 v[34:35], v[186:187], v[34:35]
	v_pk_mul_f32 v[28:29], v[188:189], v[28:29]
	v_pk_mul_f32 v[30:31], v[190:191], v[30:31]
	v_pk_mul_f32 v[24:25], v[192:193], v[24:25]
	v_pk_mul_f32 v[26:27], v[194:195], v[26:27]
	v_cvt_pk_bf16_f32 v246, v36, v37
	v_cvt_pk_bf16_f32 v247, v38, v39
	v_cvt_pk_bf16_f32 v248, v32, v33
	v_cvt_pk_bf16_f32 v249, v34, v35
	v_cvt_pk_bf16_f32 v250, v28, v29
	v_cvt_pk_bf16_f32 v251, v30, v31
	v_cvt_pk_bf16_f32 v208, v24, v25
	v_cvt_pk_bf16_f32 v209, v26, v27
	s_add_u32 s2, s2, 0x8000
	s_addc_u32 s3, s3, 0
	s_add_u32 s18, s18, 0x8000
	s_addc_u32 s19, s19, 0
	s_add_u32 s78, s78, 0x8000
	s_addc_u32 s79, s79, 0
	s_add_u32 s22, s22, 0x8000
	s_addc_u32 s23, s23, 0
	s_mov_b64 vcc, s[6:7]
	v_cndmask_b32_dpp v36, v4, v0, vcc row_ror:8 row_mask:0xf bank_mask:0xf
	v_cndmask_b32_dpp v37, v5, v1, vcc row_ror:8 row_mask:0xf bank_mask:0xf
	v_cndmask_b32_dpp v38, v6, v2, vcc row_ror:8 row_mask:0xf bank_mask:0xf
	v_cndmask_b32_dpp v39, v7, v3, vcc row_ror:8 row_mask:0xf bank_mask:0xf
	v_cndmask_b32_dpp v28, v250, v246, vcc row_ror:8 row_mask:0xf bank_mask:0xf
	v_cndmask_b32_dpp v29, v251, v247, vcc row_ror:8 row_mask:0xf bank_mask:0xf
	v_cndmask_b32_dpp v30, v208, v248, vcc row_ror:8 row_mask:0xf bank_mask:0xf
	v_cndmask_b32_dpp v31, v209, v249, vcc row_ror:8 row_mask:0xf bank_mask:0xf
	s_not_b64 vcc, s[6:7]
	v_cndmask_b32_dpp v32, v0, v4, vcc row_ror:8 row_mask:0xf bank_mask:0xf
	v_cndmask_b32_dpp v33, v1, v5, vcc row_ror:8 row_mask:0xf bank_mask:0xf
	v_cndmask_b32_dpp v34, v2, v6, vcc row_ror:8 row_mask:0xf bank_mask:0xf
	v_cndmask_b32_dpp v35, v3, v7, vcc row_ror:8 row_mask:0xf bank_mask:0xf
	v_cndmask_b32_dpp v24, v246, v250, vcc row_ror:8 row_mask:0xf bank_mask:0xf
	v_cndmask_b32_dpp v25, v247, v251, vcc row_ror:8 row_mask:0xf bank_mask:0xf
	v_cndmask_b32_dpp v26, v248, v208, vcc row_ror:8 row_mask:0xf bank_mask:0xf
	v_cndmask_b32_dpp v27, v249, v209, vcc row_ror:8 row_mask:0xf bank_mask:0xf
	global_store_dwordx4 v171, v[36:39], s[2:3]
	global_store_dwordx4 v171, v[32:35], s[18:19]
	global_store_dwordx4 v171, v[28:31], s[78:79]
	global_store_dwordx4 v171, v[24:27], s[22:23]
	s_waitcnt vmcnt(4)
	v_pk_fma_f32 v[20:21], v[20:21], v[142:143], v[238:239]
	v_pk_fma_f32 v[22:23], v[22:23], v[144:145], v[240:241]
	v_pk_fma_f32 v[16:17], v[16:17], v[150:151], v[242:243]
	v_pk_fma_f32 v[18:19], v[18:19], v[152:153], v[244:245]
	v_pk_fma_f32 v[12:13], v[12:13], v[138:139], v[196:197]
	v_pk_fma_f32 v[14:15], v[14:15], v[140:141], v[198:199]
	v_pk_fma_f32 v[8:9], v[8:9], v[146:147], v[200:201]
	v_pk_fma_f32 v[10:11], v[10:11], v[148:149], v[202:203]
	v_cvt_pk_bf16_f32 v0, v20, v21
	v_cvt_pk_bf16_f32 v1, v22, v23
	v_cvt_pk_bf16_f32 v2, v16, v17
	v_cvt_pk_bf16_f32 v3, v18, v19
	v_cvt_pk_bf16_f32 v4, v12, v13
	v_cvt_pk_bf16_f32 v5, v14, v15
	v_cvt_pk_bf16_f32 v6, v8, v9
	v_cvt_pk_bf16_f32 v7, v10, v11
	v_mul_f32_e32 v246, v21, v21
	v_mul_f32_e32 v248, v23, v23
	v_fmac_f32_e32 v246, v20, v20
	v_fmac_f32_e32 v248, v22, v22
	v_add_f32_e32 v246, v246, v248
	v_mul_f32_e32 v248, v17, v17
	v_fmac_f32_e32 v248, v16, v16
	v_add_f32_e32 v246, v246, v248
	v_mul_f32_e32 v248, v19, v19
	v_fmac_f32_e32 v248, v18, v18
	v_add_f32_e32 v246, v248, v246
	v_mul_f32_e32 v247, v13, v13
	v_mul_f32_e32 v248, v15, v15
	v_fmac_f32_e32 v247, v12, v12
	v_fmac_f32_e32 v248, v14, v14
	v_add_f32_e32 v247, v247, v248
	v_mul_f32_e32 v248, v9, v9
	v_fmac_f32_e32 v248, v8, v8
	v_add_f32_e32 v247, v247, v248
	v_mul_f32_e32 v248, v11, v11
	v_fmac_f32_e32 v248, v10, v10
	v_add_f32_e32 v247, v248, v247
	v_add_f32_e32 v246, v246, v247
	v_mov_b32_e32 v247, v246
	s_nop 1
	v_permlane16_swap_b32_e32 v246, v247
	s_nop 1
	v_add_f32_e32 v246, v246, v247
	v_mov_b32_e32 v247, v246
	s_nop 1
	v_permlane32_swap_b32_e32 v246, v247
	v_add_u32_e32 v248, s8, v223
	s_nop 0
	v_add_f32_e32 v246, v246, v247
	s_mov_b64 exec, s[44:45]
	ds_write_b32 v248, v246 offset:2816
	s_mov_b64 exec, -1
	v_pk_mul_f32 v[20:21], v[180:181], v[20:21]
	v_pk_mul_f32 v[22:23], v[182:183], v[22:23]
	v_pk_mul_f32 v[16:17], v[184:185], v[16:17]
	v_pk_mul_f32 v[18:19], v[186:187], v[18:19]
	v_pk_mul_f32 v[12:13], v[188:189], v[12:13]
	v_pk_mul_f32 v[14:15], v[190:191], v[14:15]
	v_pk_mul_f32 v[8:9], v[192:193], v[8:9]
	v_pk_mul_f32 v[10:11], v[194:195], v[10:11]
	v_cvt_pk_bf16_f32 v246, v20, v21
	v_cvt_pk_bf16_f32 v247, v22, v23
	v_cvt_pk_bf16_f32 v248, v16, v17
	v_cvt_pk_bf16_f32 v249, v18, v19
	v_cvt_pk_bf16_f32 v250, v12, v13
	v_cvt_pk_bf16_f32 v251, v14, v15
	v_cvt_pk_bf16_f32 v208, v8, v9
	v_cvt_pk_bf16_f32 v209, v10, v11
	s_add_u32 s2, s2, 0x8000
	s_addc_u32 s3, s3, 0
	s_add_u32 s18, s18, 0x8000
	s_addc_u32 s19, s19, 0
	s_add_u32 s78, s78, 0x8000
	s_addc_u32 s79, s79, 0
	s_add_u32 s22, s22, 0x8000
	s_addc_u32 s23, s23, 0
	s_mov_b64 vcc, s[6:7]
	v_cndmask_b32_dpp v20, v4, v0, vcc row_ror:8 row_mask:0xf bank_mask:0xf
	v_cndmask_b32_dpp v21, v5, v1, vcc row_ror:8 row_mask:0xf bank_mask:0xf
	v_cndmask_b32_dpp v22, v6, v2, vcc row_ror:8 row_mask:0xf bank_mask:0xf
	v_cndmask_b32_dpp v23, v7, v3, vcc row_ror:8 row_mask:0xf bank_mask:0xf
	v_cndmask_b32_dpp v12, v250, v246, vcc row_ror:8 row_mask:0xf bank_mask:0xf
	v_cndmask_b32_dpp v13, v251, v247, vcc row_ror:8 row_mask:0xf bank_mask:0xf
	v_cndmask_b32_dpp v14, v208, v248, vcc row_ror:8 row_mask:0xf bank_mask:0xf
	v_cndmask_b32_dpp v15, v209, v249, vcc row_ror:8 row_mask:0xf bank_mask:0xf
	s_not_b64 vcc, s[6:7]
	v_cndmask_b32_dpp v16, v0, v4, vcc row_ror:8 row_mask:0xf bank_mask:0xf
	v_cndmask_b32_dpp v17, v1, v5, vcc row_ror:8 row_mask:0xf bank_mask:0xf
	v_cndmask_b32_dpp v18, v2, v6, vcc row_ror:8 row_mask:0xf bank_mask:0xf
	v_cndmask_b32_dpp v19, v3, v7, vcc row_ror:8 row_mask:0xf bank_mask:0xf
	v_cndmask_b32_dpp v8, v246, v250, vcc row_ror:8 row_mask:0xf bank_mask:0xf
	v_cndmask_b32_dpp v9, v247, v251, vcc row_ror:8 row_mask:0xf bank_mask:0xf
	v_cndmask_b32_dpp v10, v248, v208, vcc row_ror:8 row_mask:0xf bank_mask:0xf
	v_cndmask_b32_dpp v11, v249, v209, vcc row_ror:8 row_mask:0xf bank_mask:0xf
	global_store_dwordx4 v171, v[20:23], s[2:3]
	global_store_dwordx4 v171, v[16:19], s[18:19]
	global_store_dwordx4 v171, v[12:15], s[78:79]
	global_store_dwordx4 v171, v[8:11], s[22:23]
	s_mov_b32 s100, 1
	s_branch .LBB0_714
